# best_v22 + 64-byte alignment (s_nop padding) of the five hot loop heads (kind0/1/2/6 K-loops, attention loop)
# baseline (speedup 1.0000x reference)
;     __device__ bool next(int i, Unit& u) const { Unit t; if (!base.next(i >> 2, t)) return false; const int br = i & 3; u.pm = br * 64 + t.pm; u.pn = br * 4 + t.pn; return true; }
; template <class Epi, class Sched, bool ALIGN_EPI = false, bool SP2 = false>
; __device__ __forceinline__ void gemm_phase(PG8_LAS unsigned char* lds, const Gemm g, const Sched& S, const Epi& E) {
;     ...
;     for (;;) {
;         const bool has_next = S.next(ui + 1, nxt);
;         const char* nA = has_next ? (const char*)g.A + (size_t)nxt.pm * tstep : cA; const char* nB = has_next ? (const char*)g.Bt + (size_t)nxt.pn * tstep : cB;
;         for (int t = 0; t < nt; t += 2) {
.LBB0_898:
	s_and_b64 vcc, exec, s[2:3]
	s_mov_b32 s20, s10
	s_mov_b32 s4, s12
	s_mov_b64 s[66:67], s[16:17]
	s_mov_b64 s[18:19], s[14:15]
	s_cbranch_vccnz .LBB0_950
	.p2alignl 6, 3212836864

; #define WAIT_BAR(N) asm volatile("s_waitcnt vmcnt(" #N ") lgkmcnt(0)\n\ts_barrier":::"memory")
;   #define DMA_K(t,slot) glds16(ksrc+(long)(t)*KVBLK*PZ,(unsigned)__builtin_amdgcn_readfirstlane(kdst+(slot)))
;   #define DMA_V(t,slot) do{ glds16(vsrc+(long)(t)*KVBLK*PZ,(unsigned)__builtin_amdgcn_readfirstlane(vdst+(slot))); glds16(vsrc+(long)SEQ*PZ+(long)(t)*KVBLK*PZ,(unsigned)__builtin_amdgcn_readfirstlane(vdst+NSLOT*SLOTB+(slot))); }while(0)
;   #define CMASK(P0,P1,t) do{int jb_=(t)-(NT-4); if(jb_>=0)cmask(P0,P1,jb_,qrel,hi);}while(0)
;   #define START(P0,P1) do{ const float rm=rowmax(P0,P1); resc=false; \
;     { const float dl=rm; mhat=fadd_s(mhat,dl); \
;       _Pragma("unroll") for(int r=0;r<16;++r){P0[r]=fsub_s(P0[r],dl);P1[r]=fsub_s(P1[r],dl);} \
;       _Pragma("unroll") for(int r=0;r<16;++r)negm[r]=-mhat; asm volatile("":"+v"(negm)); } \
;     _Pragma("unroll") for(int r=0;r<16;++r)P0[r]=__builtin_amdgcn_exp2f(P0[r]); }while(0)
;   #define ROT() do{sl_prev=sl_cur;sl_cur=sl_next;sl_next=(sl_next==(NSLOT-1)*SLOTB)?0:sl_next+SLOTB;}while(0)
;   #define CMASK(P0,P1,t) do{}while(0)
;   #define CMASK(P0,P1,t) do{int jb_=(t)-(NT-4); if(jb_>=0)cmask(P0,P1,jb_,qrel,hi);}while(0)
; template<int THRL> __device__ __forceinline__ void attn_unit(int qb,const bf16*Q,const bf16*__restrict__ K,const bf16*__restrict__ V,bf16*O,char*shm){
;     ...
;   WAIT_BAR(4);
;   qkt(pA0,pA1,Kbase,qr,negm,r32,hi);asm volatile("s_nop 15\n\ts_nop 7":"+v"(pA0),"+v"(pA1));CMASK(pA0,pA1,0);
;   START(pA0,pA1);
;   _Pragma("unroll") for(int r=0;r<16;++r)pA1[r]=__builtin_amdgcn_exp2f(pA1[r]);
;   WAIT_BAR(0);
;   DMA_K(3,0);DMA_V(1,SLOTB);
;   ROT();
;   kload8(kf,kp0+sl_cur);
;   WAIT_BAR(3);
;   s16x4 vlo[8],vhi[8]; u32x4 pw0,pw1,pw2,pw3;
.LBB0_1016:
	v_lshlrev_b32_e32 v37, 1, v36
	v_and_b32_e32 v253, 32, v37
	v_lshlrev_b32_e32 v37, 4, v36
	v_and_b32_e32 v37, 0xc0, v37
	v_lshl_or_b32 v251, v246, 8, v37
	v_add_u32_e32 v37, 0, v253
	v_add3_u32 v239, v37, v250, v251
	v_max3_f32 v37, v16, v17, v0
	v_max3_f32 v38, v18, v19, v1
	s_and_b32 s11, s15, 0x3fffffc0
	v_max3_f32 v37, v37, v2, v3
	v_max3_f32 v38, v38, v22, v23
	s_lshl_b32 s11, s11, 2
	v_max3_f32 v37, v37, v20, v21
	v_max3_f32 v38, v38, v6, v7
	s_sub_i32 s12, 0x1000, s16
	v_max3_f32 v37, v37, v4, v5
	v_max3_f32 v38, v38, v26, v27
	s_add_i32 s27, s11, 0
	v_max3_f32 v37, v37, v24, v25
	v_max3_f32 v38, v38, v10, v11
	s_add_i32 s27, s27, 0x12000
	v_max3_f32 v37, v37, v8, v9
	v_max3_f32 v38, v38, v30, v31
	s_lshr_b32 s39, s12, 6
	v_max3_f32 v37, v37, v28, v29
	v_max3_f32 v38, v38, v14, v15
	s_mov_b64 s[12:13], 0x6000
	v_max3_f32 v37, v37, v12, v13
	s_cmp_lg_u32 0, -1
	v_max_f32_e32 v37, v37, v38
	s_mov_b32 s30, 1
	v_mov_b32_e32 v38, v37
	s_nop 1
	v_permlane32_swap_b32_e32 v37, v38
	v_max_f32_e32 v37, v37, v38
	s_mov_b32 s17, 0
	v_add_f32_e32 v242, v221, v37
	v_sub_f32_e32 v0, v0, v37
	v_sub_f32_e32 v1, v1, v37
	v_sub_f32_e32 v16, v16, v37
	v_sub_f32_e32 v17, v17, v37
	v_sub_f32_e32 v18, v18, v37
	s_nop 0
	v_xor_b32_e32 v64, 0x80000000, v242
	v_mov_b32_e32 v65, v64
	v_mov_b32_e32 v66, v64
	v_mov_b32_e32 v67, v64
	v_mov_b32_e32 v68, v64
	v_mov_b32_e32 v69, v64
	v_mov_b32_e32 v70, v64
	v_mov_b32_e32 v71, v64
	v_mov_b32_e32 v72, v64
	v_mov_b32_e32 v73, v64
	v_mov_b32_e32 v74, v64
	v_mov_b32_e32 v75, v64
	v_mov_b32_e32 v76, v64
	v_mov_b32_e32 v77, v64
	v_mov_b32_e32 v78, v64
	v_mov_b32_e32 v79, v64
	s_waitcnt vmcnt(0) lgkmcnt(0)
	s_barrier
	v_exp_f32_e32 v80, v0
	v_exp_f32_e32 v81, v1
	v_lshl_add_u64 v[0:1], v[32:33], 0, s[12:13]
	s_mov_b32 s11, m0
	s_mov_b32 m0, s28
	s_nop 0
	global_load_lds_dwordx4 v[0:1], off
	s_mov_b32 m0, s11
	s_mov_b64 s[12:13], 0x2000
	s_cselect_b32 s11, 0, 0
	v_lshl_add_u64 v[0:1], v[34:35], 0, s[12:13]
	s_add_i32 s12, s11, s10
	s_add_i32 s10, s12, 0x8000
	s_mov_b32 s11, m0
	s_mov_b32 m0, s10
	s_nop 0
	global_load_lds_dwordx4 v[0:1], off
	s_mov_b32 m0, s11
	s_mov_b64 s[10:11], 0x82000
	v_lshl_add_u64 v[0:1], v[34:35], 0, s[10:11]
	s_add_i32 s12, s12, 0xe000
	s_mov_b32 s10, m0
	s_mov_b32 m0, s12
	s_nop 0
	global_load_lds_dwordx4 v[0:1], off
	s_mov_b32 m0, s10
	ds_read_b128 v[204:207], v243 offset:8192
	ds_read_b128 v[200:203], v243 offset:8704
	ds_read_b128 v[196:199], v243 offset:10240
	ds_read_b128 v[192:195], v243 offset:10752
	ds_read_b128 v[188:191], v243 offset:12288
	ds_read_b128 v[184:187], v243 offset:12800
	ds_read_b128 v[180:183], v243 offset:14336
	ds_read_b128 v[176:179], v243 offset:14848
	v_sub_f32_e32 v2, v2, v37
	v_sub_f32_e32 v19, v19, v37
	v_sub_f32_e32 v3, v3, v37
	v_sub_f32_e32 v20, v20, v37
	v_sub_f32_e32 v4, v4, v37
	v_sub_f32_e32 v21, v21, v37
	v_sub_f32_e32 v5, v5, v37
	v_sub_f32_e32 v22, v22, v37
	v_sub_f32_e32 v6, v6, v37
	v_sub_f32_e32 v23, v23, v37
	v_sub_f32_e32 v7, v7, v37
	v_sub_f32_e32 v24, v24, v37
	v_sub_f32_e32 v8, v8, v37
	v_sub_f32_e32 v25, v25, v37
	v_sub_f32_e32 v9, v9, v37
	v_sub_f32_e32 v26, v26, v37
	v_sub_f32_e32 v10, v10, v37
	v_sub_f32_e32 v27, v27, v37
	v_sub_f32_e32 v11, v11, v37
	v_sub_f32_e32 v28, v28, v37
	v_sub_f32_e32 v12, v12, v37
	v_sub_f32_e32 v29, v29, v37
	v_sub_f32_e32 v13, v13, v37
	v_sub_f32_e32 v30, v30, v37
	v_sub_f32_e32 v14, v14, v37
	v_sub_f32_e32 v31, v31, v37
	v_sub_f32_e32 v15, v15, v37
	v_exp_f32_e32 v96, v16
	v_exp_f32_e32 v97, v17
	v_exp_f32_e32 v98, v18
	v_exp_f32_e32 v99, v19
	v_exp_f32_e32 v100, v20
	v_exp_f32_e32 v101, v21
	v_exp_f32_e32 v102, v22
	v_exp_f32_e32 v103, v23
	v_exp_f32_e32 v104, v24
	v_exp_f32_e32 v105, v25
	v_exp_f32_e32 v106, v26
	v_exp_f32_e32 v107, v27
	v_exp_f32_e32 v108, v28
	v_exp_f32_e32 v109, v29
	v_exp_f32_e32 v110, v30
	v_exp_f32_e32 v111, v31
	v_exp_f32_e32 v82, v2
	v_exp_f32_e32 v83, v3
	v_exp_f32_e32 v84, v4
	v_exp_f32_e32 v85, v5
	v_exp_f32_e32 v86, v6
	v_exp_f32_e32 v87, v7
	v_exp_f32_e32 v88, v8
	v_exp_f32_e32 v89, v9
	v_exp_f32_e32 v90, v10
	v_exp_f32_e32 v91, v11
	v_exp_f32_e32 v92, v12
	v_exp_f32_e32 v93, v13
	v_exp_f32_e32 v94, v14
	v_exp_f32_e32 v95, v15
	s_waitcnt vmcnt(3) lgkmcnt(0)
	s_barrier
	v_and_b32_e32 v0, 3, v36
	s_andn2_b64 vcc, exec, s[2:3]
	v_cmp_gt_u32_e64 s[2:3], 32, v247
	v_lshlrev_b32_e32 v240, 4, v246
	v_lshl_add_u32 v252, v248, 2, s27
	v_lshlrev_b32_e32 v212, 4, v0
	s_cbranch_vccnz .LBB0_1032
	s_add_i32 s12, s14, s68
	s_lshl_b32 s12, s12, 19
	s_lshl_b64 s[10:11], s[8:9], 1
	s_and_b32 s12, s12, 0xf00000
	s_add_u32 s10, s12, s10
	v_mov_b32_e32 v213, v221
	s_addc_u32 s11, 0, s11
	v_lshl_add_u64 v[0:1], s[10:11], 0, v[212:213]
	s_lshl_b32 s10, s15, 5
	s_and_b32 s10, s10, 0x1800
	v_lshl_or_b32 v2, v224, 7, s10
	s_add_i32 s10, s69, s14
	s_and_b32 s10, s10, 31
	s_lshl_b32 s12, s10, 19
	s_lshl_b64 s[10:11], s[0:1], 1
	v_mov_b32_e32 v3, v221
	s_add_u32 s10, s10, s12
	v_mov_b32_e32 v32, v221
	v_mov_b32_e32 v33, v221
	v_mov_b32_e32 v46, v221
	v_mov_b32_e32 v47, v221
	v_lshl_add_u64 v[214:215], v[0:1], 0, v[2:3]
	s_addc_u32 s11, s11, 0
	v_mov_b32_e32 v34, v221
	v_mov_b32_e32 v35, v221
	v_mov_b32_e32 v36, v221
	v_mov_b32_e32 v37, v221
	v_mov_b32_e32 v38, v221
	v_mov_b32_e32 v39, v221
	v_mov_b32_e32 v40, v221
	v_mov_b32_e32 v41, v221
	v_mov_b32_e32 v42, v221
	v_mov_b32_e32 v43, v221
	v_mov_b32_e32 v44, v221
	v_mov_b32_e32 v45, v221
	v_mov_b64_e32 v[62:63], v[46:47]
	v_mov_b64_e32 v[16:17], v[32:33]
	v_mov_b64_e32 v[0:1], v[32:33]
	v_lshl_add_u64 v[216:217], s[10:11], 0, v[220:221]
	s_mov_b32 s10, 0
	s_movk_i32 s17, 0x4000
	s_movk_i32 s40, 0x2000
	v_mov_b32_e32 v232, 0
	s_mov_b32 s30, 6
	v_mov_b64_e32 v[60:61], v[44:45]
	v_mov_b64_e32 v[58:59], v[42:43]
	v_mov_b64_e32 v[56:57], v[40:41]
	v_mov_b64_e32 v[54:55], v[38:39]
	v_mov_b64_e32 v[52:53], v[36:37]
	v_mov_b64_e32 v[50:51], v[34:35]
	v_mov_b64_e32 v[48:49], v[32:33]
	v_mov_b64_e32 v[18:19], v[34:35]
	v_mov_b64_e32 v[20:21], v[36:37]
	v_mov_b64_e32 v[22:23], v[38:39]
	v_mov_b64_e32 v[24:25], v[40:41]
	v_mov_b64_e32 v[26:27], v[42:43]
	v_mov_b64_e32 v[28:29], v[44:45]
	v_mov_b64_e32 v[30:31], v[46:47]
	v_mov_b64_e32 v[2:3], v[34:35]
	v_mov_b64_e32 v[4:5], v[36:37]
	v_mov_b64_e32 v[6:7], v[38:39]
	v_mov_b64_e32 v[8:9], v[40:41]
	v_mov_b64_e32 v[10:11], v[42:43]
	v_mov_b64_e32 v[12:13], v[44:45]
	v_mov_b64_e32 v[14:15], v[46:47]
	.p2alignl 6, 3212836864

; template <class Epi, class Sched, bool ALIGN_EPI = false, bool SP2 = false>
; __device__ __forceinline__ void gemm_phase(PG8_LAS unsigned char* lds, const Gemm g, const Sched& S, const Epi& E) {
;     ...
;         const char* nA = has_next ? (const char*)g.A + (size_t)nxt.pm * tstep : cA; const char* nB = has_next ? (const char*)g.Bt + (size_t)nxt.pn * tstep : cB;
;         for (int t = 0; t < nt; t += 2) {
;             const bool last = (t == nt - 2);
;             const char* a1 = cA + (size_t)(t + 1) * kstep;
;             const char* a2 = last ? nA : cA + (size_t)(t + 2) * kstep; const char* b2 = last ? nB : cB + (size_t)(t + 2) * kstep;
;             const char* a3 = a2 + kstep; const char* b3 = b2 + kstep;
;     ...
; #pragma unroll
;         for (int a = 0; a < 2; ++a)
; #pragma unroll
;             for (int b = 0; b < 2; ++b)
; #pragma unroll
;                 for (int m = 0; m < 4; ++m)
; #pragma unroll
;                     for (int n = 0; n < 2; ++n) acc[a][b][m][n] = (f32x4){0.f, 0.f, 0.f, 0.f};
;         cur = nxt; cA = nA; cB = nB; ++ui;
.LBB0_1129:
	s_ashr_i32 s79, s78, 31
	s_lshl_b64 s[22:23], s[78:79], 19
	v_readlane_b32 s5, v255, 15
	s_add_u32 s80, s5, s22
	s_addc_u32 s81, s61, s23
	s_and_b64 s[22:23], s[2:3], exec
	s_cselect_b32 s5, s81, s7
	s_cselect_b32 s9, s80, s6
	s_ashr_i32 s77, s76, 31
	s_lshl_b64 s[22:23], s[76:77], 19
	s_add_u32 s82, s55, s22
	s_addc_u32 s83, s56, s23
	s_and_b64 s[22:23], s[2:3], exec
	s_cselect_b32 s22, s83, s11
	s_cselect_b32 s23, s82, s10
	s_add_u32 s6, s6, 0xc000
	s_addc_u32 s7, s7, 0
	s_add_u32 s30, s10, 0x10000
	v_mov_b32_e32 v0, 0
	s_addc_u32 s37, s11, 0
	s_mov_b32 s40, -2
	v_mov_b32_e32 v1, v0
	v_mov_b32_e32 v2, v0
	v_mov_b32_e32 v3, v0
	v_mov_b32_e32 v4, v0
	v_mov_b32_e32 v5, v0
	v_mov_b32_e32 v6, v0
	v_mov_b32_e32 v7, v0
	v_mov_b32_e32 v28, v0
	v_mov_b32_e32 v29, v0
	v_mov_b32_e32 v30, v0
	v_mov_b32_e32 v31, v0
	v_mov_b32_e32 v36, v0
	v_mov_b32_e32 v37, v0
	v_mov_b32_e32 v38, v0
	v_mov_b32_e32 v39, v0
	v_mov_b32_e32 v64, v0
	v_mov_b32_e32 v65, v0
	v_mov_b32_e32 v66, v0
	v_mov_b32_e32 v67, v0
	v_mov_b32_e32 v68, v0
	v_mov_b32_e32 v69, v0
	v_mov_b32_e32 v70, v0
	v_mov_b32_e32 v71, v0
	v_mov_b32_e32 v80, v0
	v_mov_b32_e32 v81, v0
	v_mov_b32_e32 v82, v0
	v_mov_b32_e32 v83, v0
	v_mov_b32_e32 v84, v0
	v_mov_b32_e32 v85, v0
	v_mov_b32_e32 v86, v0
	v_mov_b32_e32 v87, v0
	v_mov_b32_e32 v8, v0
	v_mov_b32_e32 v9, v0
	v_mov_b32_e32 v10, v0
	v_mov_b32_e32 v11, v0
	v_mov_b32_e32 v12, v0
	v_mov_b32_e32 v13, v0
	v_mov_b32_e32 v14, v0
	v_mov_b32_e32 v15, v0
	v_mov_b32_e32 v40, v0
	v_mov_b32_e32 v41, v0
	v_mov_b32_e32 v42, v0
	v_mov_b32_e32 v43, v0
	v_mov_b32_e32 v44, v0
	v_mov_b32_e32 v45, v0
	v_mov_b32_e32 v46, v0
	v_mov_b32_e32 v47, v0
	v_mov_b32_e32 v72, v0
	v_mov_b32_e32 v73, v0
	v_mov_b32_e32 v74, v0
	v_mov_b32_e32 v75, v0
	v_mov_b32_e32 v76, v0
	v_mov_b32_e32 v77, v0
	v_mov_b32_e32 v78, v0
	v_mov_b32_e32 v79, v0
	v_mov_b32_e32 v88, v0
	v_mov_b32_e32 v89, v0
	v_mov_b32_e32 v90, v0
	v_mov_b32_e32 v91, v0
	v_mov_b32_e32 v92, v0
	v_mov_b32_e32 v93, v0
	v_mov_b32_e32 v94, v0
	v_mov_b32_e32 v95, v0
	v_mov_b32_e32 v96, v0
	v_mov_b32_e32 v97, v0
	v_mov_b32_e32 v98, v0
	v_mov_b32_e32 v99, v0
	v_mov_b32_e32 v100, v0
	v_mov_b32_e32 v101, v0
	v_mov_b32_e32 v102, v0
	v_mov_b32_e32 v103, v0
	v_mov_b32_e32 v112, v0
	v_mov_b32_e32 v113, v0
	v_mov_b32_e32 v114, v0
	v_mov_b32_e32 v115, v0
	v_mov_b32_e32 v116, v0
	v_mov_b32_e32 v117, v0
	v_mov_b32_e32 v118, v0
	v_mov_b32_e32 v119, v0
	v_mov_b32_e32 v128, v0
	v_mov_b32_e32 v129, v0
	v_mov_b32_e32 v130, v0
	v_mov_b32_e32 v131, v0
	v_mov_b32_e32 v132, v0
	v_mov_b32_e32 v133, v0
	v_mov_b32_e32 v134, v0
	v_mov_b32_e32 v135, v0
	v_mov_b32_e32 v144, v0
	v_mov_b32_e32 v145, v0
	v_mov_b32_e32 v146, v0
	v_mov_b32_e32 v147, v0
	v_mov_b32_e32 v148, v0
	v_mov_b32_e32 v149, v0
	v_mov_b32_e32 v150, v0
	v_mov_b32_e32 v151, v0
	v_mov_b32_e32 v104, v0
	v_mov_b32_e32 v105, v0
	v_mov_b32_e32 v106, v0
	v_mov_b32_e32 v107, v0
	v_mov_b32_e32 v108, v0
	v_mov_b32_e32 v109, v0
	v_mov_b32_e32 v110, v0
	v_mov_b32_e32 v111, v0
	v_mov_b32_e32 v120, v0
	v_mov_b32_e32 v121, v0
	v_mov_b32_e32 v122, v0
	v_mov_b32_e32 v123, v0
	v_mov_b32_e32 v124, v0
	v_mov_b32_e32 v125, v0
	v_mov_b32_e32 v126, v0
	v_mov_b32_e32 v127, v0
	v_mov_b32_e32 v136, v0
	v_mov_b32_e32 v137, v0
	v_mov_b32_e32 v138, v0
	v_mov_b32_e32 v139, v0
	v_mov_b32_e32 v140, v0
	v_mov_b32_e32 v141, v0
	v_mov_b32_e32 v142, v0
	v_mov_b32_e32 v143, v0
	v_mov_b32_e32 v152, v0
	v_mov_b32_e32 v153, v0
	v_mov_b32_e32 v154, v0
	v_mov_b32_e32 v155, v0
	v_mov_b32_e32 v156, v0
	v_mov_b32_e32 v157, v0
	v_mov_b32_e32 v158, v0
	v_mov_b32_e32 v159, v0
	.p2alignl 6, 3212836864

; template <class Epi, class Sched, bool ALIGN_EPI = false, bool SP2 = false>
; __device__ __forceinline__ void gemm_phase(PG8_LAS unsigned char* lds, const Gemm g, const Sched& S, const Epi& E) {
;     ...
;         for (int t = 0; t < nt; t += 2) {
;             const bool last = (t == nt - 2);
;             const char* a1 = cA + (size_t)(t + 1) * kstep;
;             const char* a2 = last ? nA : cA + (size_t)(t + 2) * kstep; const char* b2 = last ? nB : cB + (size_t)(t + 2) * kstep;
;             const char* a3 = a2 + kstep; const char* b3 = b2 + kstep;
;     ...
; #pragma unroll
;         for (int a = 0; a < 2; ++a)
; #pragma unroll
;             for (int b = 0; b < 2; ++b)
; #pragma unroll
;                 for (int m = 0; m < 4; ++m)
; #pragma unroll
;                     for (int n = 0; n < 2; ++n) acc[a][b][m][n] = (f32x4){0.f, 0.f, 0.f, 0.f};
.LBB0_1321:
	s_add_u32 s16, s16, 0xc000
	s_addc_u32 s17, s17, 0
	s_add_u32 s66, s18, 0x10000
	v_mov_b32_e32 v0, 0
	s_addc_u32 s67, s19, 0
	s_mov_b32 s18, 0
	v_mov_b32_e32 v1, v0
	v_mov_b32_e32 v2, v0
	v_mov_b32_e32 v3, v0
	v_mov_b32_e32 v4, v0
	v_mov_b32_e32 v5, v0
	v_mov_b32_e32 v6, v0
	v_mov_b32_e32 v7, v0
	v_mov_b32_e32 v16, v0
	v_mov_b32_e32 v17, v0
	v_mov_b32_e32 v18, v0
	v_mov_b32_e32 v19, v0
	v_mov_b32_e32 v20, v0
	v_mov_b32_e32 v21, v0
	v_mov_b32_e32 v22, v0
	v_mov_b32_e32 v23, v0
	v_mov_b32_e32 v32, v0
	v_mov_b32_e32 v33, v0
	v_mov_b32_e32 v34, v0
	v_mov_b32_e32 v35, v0
	v_mov_b32_e32 v36, v0
	v_mov_b32_e32 v37, v0
	v_mov_b32_e32 v38, v0
	v_mov_b32_e32 v39, v0
	v_mov_b32_e32 v48, v0
	v_mov_b32_e32 v49, v0
	v_mov_b32_e32 v50, v0
	v_mov_b32_e32 v51, v0
	v_mov_b32_e32 v52, v0
	v_mov_b32_e32 v53, v0
	v_mov_b32_e32 v54, v0
	v_mov_b32_e32 v55, v0
	v_mov_b32_e32 v8, v0
	v_mov_b32_e32 v9, v0
	v_mov_b32_e32 v10, v0
	v_mov_b32_e32 v11, v0
	v_mov_b32_e32 v12, v0
	v_mov_b32_e32 v13, v0
	v_mov_b32_e32 v14, v0
	v_mov_b32_e32 v15, v0
	v_mov_b32_e32 v24, v0
	v_mov_b32_e32 v25, v0
	v_mov_b32_e32 v26, v0
	v_mov_b32_e32 v27, v0
	v_mov_b32_e32 v28, v0
	v_mov_b32_e32 v29, v0
	v_mov_b32_e32 v30, v0
	v_mov_b32_e32 v31, v0
	v_mov_b32_e32 v40, v0
	v_mov_b32_e32 v41, v0
	v_mov_b32_e32 v42, v0
	v_mov_b32_e32 v43, v0
	v_mov_b32_e32 v44, v0
	v_mov_b32_e32 v45, v0
	v_mov_b32_e32 v46, v0
	v_mov_b32_e32 v47, v0
	v_mov_b32_e32 v56, v0
	v_mov_b32_e32 v57, v0
	v_mov_b32_e32 v58, v0
	v_mov_b32_e32 v59, v0
	v_mov_b32_e32 v60, v0
	v_mov_b32_e32 v61, v0
	v_mov_b32_e32 v62, v0
	v_mov_b32_e32 v63, v0
	v_mov_b32_e32 v64, v0
	v_mov_b32_e32 v65, v0
	v_mov_b32_e32 v66, v0
	v_mov_b32_e32 v67, v0
	v_mov_b32_e32 v68, v0
	v_mov_b32_e32 v69, v0
	v_mov_b32_e32 v70, v0
	v_mov_b32_e32 v71, v0
	v_mov_b32_e32 v88, v0
	v_mov_b32_e32 v89, v0
	v_mov_b32_e32 v90, v0
	v_mov_b32_e32 v91, v0
	v_mov_b32_e32 v92, v0
	v_mov_b32_e32 v93, v0
	v_mov_b32_e32 v94, v0
	v_mov_b32_e32 v95, v0
	v_mov_b32_e32 v112, v0
	v_mov_b32_e32 v113, v0
	v_mov_b32_e32 v114, v0
	v_mov_b32_e32 v115, v0
	v_mov_b32_e32 v116, v0
	v_mov_b32_e32 v117, v0
	v_mov_b32_e32 v118, v0
	v_mov_b32_e32 v119, v0
	v_mov_b32_e32 v132, v0
	v_mov_b32_e32 v133, v0
	v_mov_b32_e32 v134, v0
	v_mov_b32_e32 v135, v0
	v_mov_b32_e32 v140, v0
	v_mov_b32_e32 v141, v0
	v_mov_b32_e32 v142, v0
	v_mov_b32_e32 v143, v0
	v_mov_b32_e32 v72, v0
	v_mov_b32_e32 v73, v0
	v_mov_b32_e32 v74, v0
	v_mov_b32_e32 v75, v0
	v_mov_b32_e32 v76, v0
	v_mov_b32_e32 v77, v0
	v_mov_b32_e32 v78, v0
	v_mov_b32_e32 v79, v0
	v_mov_b32_e32 v96, v0
	v_mov_b32_e32 v97, v0
	v_mov_b32_e32 v98, v0
	v_mov_b32_e32 v99, v0
	v_mov_b32_e32 v100, v0
	v_mov_b32_e32 v101, v0
	v_mov_b32_e32 v102, v0
	v_mov_b32_e32 v103, v0
	v_mov_b32_e32 v120, v0
	v_mov_b32_e32 v121, v0
	v_mov_b32_e32 v122, v0
	v_mov_b32_e32 v123, v0
	v_mov_b32_e32 v124, v0
	v_mov_b32_e32 v125, v0
	v_mov_b32_e32 v126, v0
	v_mov_b32_e32 v127, v0
	v_mov_b32_e32 v144, v0
	v_mov_b32_e32 v145, v0
	v_mov_b32_e32 v146, v0
	v_mov_b32_e32 v147, v0
	v_mov_b32_e32 v148, v0
	v_mov_b32_e32 v149, v0
	v_mov_b32_e32 v150, v0
	v_mov_b32_e32 v151, v0
	.p2alignl 6, 3212836864

; template <class Epi, class Sched, bool ALIGN_EPI = false, bool SP2 = false>
; __device__ __forceinline__ void gemm_phase(PG8_LAS unsigned char* lds, const Gemm g, const Sched& S, const Epi& E) {
;     ...
;         const char* nA = has_next ? (const char*)g.A + (size_t)nxt.pm * tstep : cA; const char* nB = has_next ? (const char*)g.Bt + (size_t)nxt.pn * tstep : cB;
;         for (int t = 0; t < nt; t += 2) {
;             const bool last = (t == nt - 2);
;             const char* a1 = cA + (size_t)(t + 1) * kstep;
;             const char* a2 = last ? nA : cA + (size_t)(t + 2) * kstep; const char* b2 = last ? nB : cB + (size_t)(t + 2) * kstep;
;             const char* a3 = a2 + kstep; const char* b3 = b2 + kstep;
;     ...
; #pragma unroll
;         for (int a = 0; a < 2; ++a)
; #pragma unroll
;             for (int b = 0; b < 2; ++b)
; #pragma unroll
;                 for (int m = 0; m < 4; ++m)
; #pragma unroll
;                     for (int n = 0; n < 2; ++n) acc[a][b][m][n] = (f32x4){0.f, 0.f, 0.f, 0.f};
;         cur = nxt; cA = nA; cB = nB; ++ui;
.LBB0_1355:
	s_ashr_i32 s11, s10, 31
	s_lshl_b64 s[12:13], s[10:11], 19
	s_add_u32 s12, s22, s12
	s_addc_u32 s13, s23, s13
	s_and_b64 s[14:15], s[2:3], exec
	s_cselect_b32 s11, s13, s19
	s_cselect_b32 s40, s12, s18
	s_ashr_i32 s9, s8, 31
	s_lshl_b64 s[14:15], s[8:9], 19
	s_add_u32 s14, s27, s14
	s_addc_u32 s15, s28, s15
	s_and_b64 s[62:63], s[2:3], exec
	s_cselect_b32 s9, s15, s21
	s_cselect_b32 s61, s14, s20
	s_add_u32 s18, s18, 0xc000
	s_addc_u32 s19, s19, 0
	s_add_u32 s66, s20, 0x10000
	v_mov_b32_e32 v0, 0
	s_addc_u32 s67, s21, 0
	s_mov_b32 s68, -2
	v_mov_b32_e32 v1, v0
	v_mov_b32_e32 v2, v0
	v_mov_b32_e32 v3, v0
	v_mov_b32_e32 v4, v0
	v_mov_b32_e32 v5, v0
	v_mov_b32_e32 v6, v0
	v_mov_b32_e32 v7, v0
	v_mov_b32_e32 v16, v0
	v_mov_b32_e32 v17, v0
	v_mov_b32_e32 v18, v0
	v_mov_b32_e32 v19, v0
	v_mov_b32_e32 v20, v0
	v_mov_b32_e32 v21, v0
	v_mov_b32_e32 v22, v0
	v_mov_b32_e32 v23, v0
	v_mov_b32_e32 v32, v0
	v_mov_b32_e32 v33, v0
	v_mov_b32_e32 v34, v0
	v_mov_b32_e32 v35, v0
	v_mov_b32_e32 v36, v0
	v_mov_b32_e32 v37, v0
	v_mov_b32_e32 v38, v0
	v_mov_b32_e32 v39, v0
	v_mov_b32_e32 v48, v0
	v_mov_b32_e32 v49, v0
	v_mov_b32_e32 v50, v0
	v_mov_b32_e32 v51, v0
	v_mov_b32_e32 v52, v0
	v_mov_b32_e32 v53, v0
	v_mov_b32_e32 v54, v0
	v_mov_b32_e32 v55, v0
	v_mov_b32_e32 v8, v0
	v_mov_b32_e32 v9, v0
	v_mov_b32_e32 v10, v0
	v_mov_b32_e32 v11, v0
	v_mov_b32_e32 v12, v0
	v_mov_b32_e32 v13, v0
	v_mov_b32_e32 v14, v0
	v_mov_b32_e32 v15, v0
	v_mov_b32_e32 v24, v0
	v_mov_b32_e32 v25, v0
	v_mov_b32_e32 v26, v0
	v_mov_b32_e32 v27, v0
	v_mov_b32_e32 v28, v0
	v_mov_b32_e32 v29, v0
	v_mov_b32_e32 v30, v0
	v_mov_b32_e32 v31, v0
	v_mov_b32_e32 v40, v0
	v_mov_b32_e32 v41, v0
	v_mov_b32_e32 v42, v0
	v_mov_b32_e32 v43, v0
	v_mov_b32_e32 v44, v0
	v_mov_b32_e32 v45, v0
	v_mov_b32_e32 v46, v0
	v_mov_b32_e32 v47, v0
	v_mov_b32_e32 v56, v0
	v_mov_b32_e32 v57, v0
	v_mov_b32_e32 v58, v0
	v_mov_b32_e32 v59, v0
	v_mov_b32_e32 v60, v0
	v_mov_b32_e32 v61, v0
	v_mov_b32_e32 v62, v0
	v_mov_b32_e32 v63, v0
	v_mov_b32_e32 v64, v0
	v_mov_b32_e32 v65, v0
	v_mov_b32_e32 v66, v0
	v_mov_b32_e32 v67, v0
	v_mov_b32_e32 v68, v0
	v_mov_b32_e32 v69, v0
	v_mov_b32_e32 v70, v0
	v_mov_b32_e32 v71, v0
	v_mov_b32_e32 v80, v0
	v_mov_b32_e32 v81, v0
	v_mov_b32_e32 v82, v0
	v_mov_b32_e32 v83, v0
	v_mov_b32_e32 v84, v0
	v_mov_b32_e32 v85, v0
	v_mov_b32_e32 v86, v0
	v_mov_b32_e32 v87, v0
	v_mov_b32_e32 v96, v0
	v_mov_b32_e32 v97, v0
	v_mov_b32_e32 v98, v0
	v_mov_b32_e32 v99, v0
	v_mov_b32_e32 v100, v0
	v_mov_b32_e32 v101, v0
	v_mov_b32_e32 v102, v0
	v_mov_b32_e32 v103, v0
	v_mov_b32_e32 v112, v0
	v_mov_b32_e32 v113, v0
	v_mov_b32_e32 v114, v0
	v_mov_b32_e32 v115, v0
	v_mov_b32_e32 v116, v0
	v_mov_b32_e32 v117, v0
	v_mov_b32_e32 v118, v0
	v_mov_b32_e32 v119, v0
	v_mov_b32_e32 v72, v0
	v_mov_b32_e32 v73, v0
	v_mov_b32_e32 v74, v0
	v_mov_b32_e32 v75, v0
	v_mov_b32_e32 v76, v0
	v_mov_b32_e32 v77, v0
	v_mov_b32_e32 v78, v0
	v_mov_b32_e32 v79, v0
	v_mov_b32_e32 v88, v0
	v_mov_b32_e32 v89, v0
	v_mov_b32_e32 v90, v0
	v_mov_b32_e32 v91, v0
	v_mov_b32_e32 v92, v0
	v_mov_b32_e32 v93, v0
	v_mov_b32_e32 v94, v0
	v_mov_b32_e32 v95, v0
	v_mov_b32_e32 v104, v0
	v_mov_b32_e32 v105, v0
	v_mov_b32_e32 v106, v0
	v_mov_b32_e32 v107, v0
	v_mov_b32_e32 v108, v0
	v_mov_b32_e32 v109, v0
	v_mov_b32_e32 v110, v0
	v_mov_b32_e32 v111, v0
	v_mov_b32_e32 v120, v0
	v_mov_b32_e32 v121, v0
	v_mov_b32_e32 v122, v0
	v_mov_b32_e32 v123, v0
	v_mov_b32_e32 v124, v0
	v_mov_b32_e32 v125, v0
	v_mov_b32_e32 v126, v0
	v_mov_b32_e32 v127, v0
	.p2alignl 6, 3212836864
